# one static priority raise per phase: waves 4-7 in R7_CA, waves 0-3 in R7_CB (reset at phase end)
# speedup vs baseline: 1.0007x; 1.0007x over previous
; __device__ __forceinline__ int ltid() { int t = threadIdx.x; asm volatile("" : "+v"(t)); return t; }
; __device__ __forceinline__ void ph_r7_cb(const P& p, int win, char* smem) {
;   bfr* Sh = (bfr*)smem; bfr* Sl = Sh + 2 * 16 * CS; bfr* VT = Sl + 2 * 16 * CS;
;   const bfr* WB = p.H; const bfr* RK = (const bfr*)(p.ACT + A_RKVZ); bfr* SST = (bfr*)(p.ACT + A_SST);
;   const int tid = ltid(), lane = tid & 63, w = tid >> 6, l15 = lane & 15, q4 = lane >> 4;
;   const int c0 = win * 20;
;   for (int it = xcd_swz(); it < 256; it += gridDim.x) {
;     const int d = it & 1, b = it >> 7, h = (it >> 3) & 15, rg = (it >> 1) & 3, chain = (b * 16 + h) * 2 + d;
;     bfr* Y = d ? R7_Y2 : (bfr*)(p.ACT + A_Y);
;     bfr* sst = SST + (size_t)(chain * 4 + rg) * 2048;
;     __syncthreads();
;     if (tid < 256) { const int hl = tid >> 7, e = tid & 127, rr = e >> 3, c8 = e & 7; uint4 v = uint4{0u, 0u, 0u, 0u};
;       if (win > 0) v = *(const uint4*)(sst + hl * 1024 + rr * 64 + c8 * 8);
;       *(uint4*)((hl ? Sl : Sh) + rr * CS + c8 * 8) = v; }
;     const int vtau = tid >> 3, vp = tid & 7;
;     { const int row = rowmap(d, b, 64 * c0 + vtau); unsigned vv = *(const unsigned*)(RK + (size_t)row * 4096 + 2048 + h * 64 + rg * 16 + 2 * vp);
;       VT[(2 * vp) * CS + vtau] = (bfr)(vv & 0xffff); VT[(2 * vp + 1) * CS + vtau] = (bfr)(vv >> 16); }
;     const bfr* bbase = WB + (size_t)(chain * 20) * 16384 + (w < 4 ? 8192 + (16 * w + l15) * 64 : (16 * (w - 4) + l15) * 64) + 8 * q4;
;     bf16x8 rb1[4][2], rb2[4][2]; unsigned rv[4];
;     ...
;     CB_LOAD(0, 0) CB_LOAD(1, 1) CB_LOAD(2, 2) CB_LOAD(3, 3)
.LBB0_137:
	s_andn2_b64 vcc, exec, s[6:7]
	s_cbranch_vccnz .LBB0_182
	v_readlane_b32 s6, v251, 21
	v_readlane_b32 s7, v251, 22
	v_mov_b32_e32 v0, v168
	s_andn2_b64 vcc, exec, s[6:7]
	s_cbranch_vccnz .LBB0_182
	v_readfirstlane_b32 s6, v168
	s_lshr_b32 s6, s6, 6
	s_cmp_ge_u32 s6, 4
	s_cbranch_scc1 .Lprio_cb
	s_setprio 1
.Lprio_cb:
	v_readlane_b32 s8, v253, 26
	v_ashrrev_i32_e32 v69, 3, v0
	s_mul_i32 s19, s18, 0x500
	v_mov_b32_e32 v9, s8
	s_movk_i32 s8, 0x80
	v_and_b32_e32 v3, 15, v0
	v_bfe_u32 v5, v0, 4, 2
	v_ashrrev_i32_e32 v7, 6, v0
	v_cmp_gt_i32_e64 s[40:41], s65, v0
	v_bfe_u32 v4, v0, 3, 4
	v_and_b32_e32 v6, 7, v0
	v_lshlrev_b32_e32 v8, 3, v0
	v_cmp_gt_u32_e32 vcc, s8, v0
	v_add_u32_e32 v71, s19, v69
	v_lshlrev_b32_e32 v0, 1, v0
	v_cndmask_b32_e64 v9, v9, 0, vcc
	v_cmp_lt_i32_e32 vcc, s15, v71
	v_and_b32_e32 v70, 14, v0
	v_add_u32_e32 v90, 64, v71
	v_lshlrev_b32_e32 v68, 6, v4
	s_waitcnt vmcnt(0)
	v_mad_u32_u24 v10, v4, s14, v9
	v_cndmask_b32_e32 v4, v176, v177, vcc
	v_mul_u32_u24_e32 v0, 0x48, v70
	v_cmp_lt_i32_e32 vcc, s15, v90
	v_add_u32_e32 v92, 0x80, v71
	v_lshlrev_b32_e32 v12, 1, v0
	v_cndmask_b32_e32 v0, v176, v177, vcc
	v_cmp_lt_i32_e32 vcc, s15, v92
	v_add_u32_e32 v94, 0xc0, v71
	v_sub_u32_e32 v91, v0, v90
	v_cndmask_b32_e32 v0, v176, v177, vcc
	v_cmp_lt_i32_e32 vcc, s15, v94
	s_mov_b32 s8, 0x7fffff00
	v_sub_u32_e32 v93, v0, v92
	v_cndmask_b32_e32 v0, v176, v177, vcc
	v_cmp_gt_u32_e32 vcc, s8, v71
	v_sub_u32_e32 v95, v0, v94
	v_add_u32_e32 v96, 0x100, v71
	v_cndmask_b32_e32 v0, v176, v177, vcc
	v_lshlrev_b32_e32 v14, 10, v7
	v_lshlrev_b32_e32 v15, 6, v3
	v_sub_u32_e32 v97, v0, v96
	v_lshl_or_b32 v98, v7, 4, v3
	v_cmp_gt_i32_e32 vcc, 4, v7
	v_mov_b32_e32 v0, 0x2000
	v_cmp_lt_i32_e64 s[42:43], 3, v7
	v_add_u32_e32 v16, s19, v98
	v_cndmask_b32_e32 v7, v250, v0, vcc
	v_or_b32_e32 v0, v14, v15
	v_mul_u32_u24_e32 v3, 0x48, v3
	v_and_b32_e32 v66, 0xfffffc00, v8
	v_lshlrev_b32_e32 v2, 3, v6
	v_lshlrev_b32_e32 v11, 4, v6
	v_and_b32_e32 v6, 56, v8
	v_add_u32_e32 v8, v0, v7
	v_lshlrev_b32_e32 v0, 4, v5
	v_lshlrev_b32_e32 v3, 1, v3
	s_movk_i32 s8, 0x120
	v_add_u32_e32 v103, 0x3c0, v16
	v_add3_u32 v100, 0, v0, v3
	v_mad_u32_u24 v3, v5, s8, v98
	v_cmp_lt_i32_e32 vcc, s15, v103
	v_add_u32_e32 v105, 0x400, v16
	v_lshl_add_u32 v101, v3, 1, 0
	v_cndmask_b32_e32 v3, v176, v177, vcc
	v_cmp_lt_i32_e32 vcc, s15, v105
	v_add_u32_e32 v107, 0x440, v16
	v_sub_u32_e32 v104, v3, v103
	v_cndmask_b32_e32 v3, v176, v177, vcc
	v_cmp_lt_i32_e32 vcc, s15, v107
	v_add_u32_e32 v109, 0x480, v16
	v_sub_u32_e32 v106, v3, v105
	v_cndmask_b32_e32 v3, v176, v177, vcc
	v_cmp_lt_i32_e32 vcc, s15, v109
	v_ashrrev_i32_e32 v9, 31, v8
	v_sub_u32_e32 v108, v3, v107
	v_cndmask_b32_e32 v3, v176, v177, vcc
	v_lshl_add_u64 v[8:9], v[8:9], 1, s[24:25]
	v_sub_u32_e32 v110, v3, v109
	v_add_u32_e32 v3, v7, v14
	v_lshl_add_u64 v[72:73], v[8:9], 0, v[0:1]
	v_or_b32_e32 v8, v3, v15
	v_ashrrev_i32_e32 v9, 31, v8
	v_lshlrev_b64 v[8:9], 1, v[8:9]
	s_cmp_gt_i32 s18, 0
	v_sub_u32_e32 v88, v4, v71
	v_lshlrev_b32_e32 v13, 1, v69
	v_lshlrev_b32_e32 v4, 2, v5
	v_or_b32_e32 v8, v8, v0
	v_readlane_b32 s8, v253, 13
	s_cselect_b64 s[6:7], -1, 0
	v_ashrrev_i32_e32 v67, 31, v66
	v_add3_u32 v89, 0, v12, v13
	v_lshl_add_u32 v99, v6, 1, v10
	v_add3_u32 v102, 0, v13, v12
	v_lshl_add_u64 v[74:75], s[24:25], 0, v[8:9]
	s_mul_i32 s50, s18, 0xfffffb00
	v_sub_u32_e32 v111, 0, v98
	v_sub_u32_e32 v112, 0, v69
	v_lshlrev_b32_e32 v76, 1, v2
	v_add_u32_e32 v113, v10, v11
	v_lshlrev_b32_e32 v78, 1, v4
	v_lshlrev_b32_e32 v80, 1, v6
	v_readlane_b32 s9, v253, 14
	v_readlane_b32 s51, v253, 21
	s_branch .LBB0_141

; __device__ __forceinline__ int ltid() { int t = threadIdx.x; asm volatile("" : "+v"(t)); return t; }
; __device__ __forceinline__ void ph_r7_ca(const P& p, int j, int win, char* smem) {
;   float* LW = (float*)(smem + 7 * 9216); float* AT = (float*)(smem + 9 * 9216); float* WL = (float*)(smem + 14 * 9216);
;   const bfr* RK = (const bfr*)(p.ACT + A_RKVZ); const bfr* WMb = (const bfr*)(p.ACT + A_WM); const bfr* AMb = (const bfr*)(p.ACT + A_AM);
;   float* BON = (float*)(p.ACT + A_BON); bfr* WB = p.H;
;   const float* kkp = p.r7_k_k + (size_t)j * 1024; const float* kap = p.r7_k_a + (size_t)j * 1024; const float* rkp = p.r7_r_k + (size_t)j * 1024;
;   const int tid = ltid(), lane = tid & 63, w = tid >> 6, l15 = lane & 15, q4 = lane >> 4, ti = w >> 1, tj0 = (w & 1) * 2;
;   const int c0 = win * 20;
.LBB0_183:
	s_andn2_b64 vcc, exec, s[6:7]
	s_cbranch_vccnz .LBB0_275
	v_readlane_b32 s6, v251, 25
	v_readlane_b32 s7, v251, 26
	s_waitcnt vmcnt(0)
	v_mov_b32_e32 v35, v168
	s_andn2_b64 vcc, exec, s[6:7]
	s_cbranch_vccnz .LBB0_275
	v_readfirstlane_b32 s6, v168
	s_lshr_b32 s6, s6, 6
	s_cmp_ge_u32 s6, 4
	s_cbranch_scc0 .Lprio_ca
	s_setprio 1
.Lprio_ca:
	v_readlane_b32 s6, v254, 57
	v_readlane_b32 s7, v254, 58
	s_mov_b32 s8, s6
	s_ashr_i32 s9, s6, 31
	s_lshl_b64 s[6:7], s[8:9], 12
	v_readlane_b32 s40, v253, 57
	v_and_b32_e32 v4, 64, v175
	v_readlane_b32 s41, v253, 58
	s_add_u32 s92, s40, s6
	v_xor_b32_e32 v2, 1, v175
	v_add_u32_e32 v4, 64, v4
	v_readlane_b32 s42, v253, 59
	s_addc_u32 s93, s41, s7
	v_cmp_lt_i32_e32 vcc, v2, v4
	v_readlane_b32 s43, v253, 60
	s_add_u32 s96, s42, s6
	v_cndmask_b32_e32 v2, v175, v2, vcc
	v_readlane_b32 s44, v253, 61
	v_readlane_b32 s48, v254, 1
	s_addc_u32 s97, s43, s7
	v_lshlrev_b32_e32 v57, 2, v2
	v_xor_b32_e32 v2, 2, v175
	v_readlane_b32 s45, v253, 62
	v_readlane_b32 s49, v254, 2
	s_add_u32 s48, s44, s6
	s_mov_b32 s6, s8
	v_cmp_lt_i32_e32 vcc, v2, v4
	v_readlane_b32 s47, v254, 0
	v_readlane_b32 s50, v254, 3
	v_readlane_b32 s51, v254, 4
	v_readlane_b32 s52, v254, 5
	v_readlane_b32 s53, v254, 6
	v_readlane_b32 s54, v254, 7
	v_readlane_b32 s55, v254, 8
	s_addc_u32 s49, s45, s7
	v_writelane_b32 v254, s6, 57
	v_cndmask_b32_e32 v2, v175, v2, vcc
	v_lshlrev_b32_e32 v58, 2, v2
	v_writelane_b32 v254, s7, 58
	v_cmp_gt_i32_e64 s[6:7], 64, v35
	v_xor_b32_e32 v2, 4, v175
	v_ashrrev_i32_e32 v52, 3, v35
	v_writelane_b32 v254, s6, 61
	v_cmp_lt_i32_e32 vcc, v2, v4
	v_ashrrev_i32_e32 v3, 6, v35
	v_bfe_u32 v39, v35, 4, 2
	v_and_b32_e32 v53, -16, v52
	v_writelane_b32 v254, s7, 62
	v_and_b32_e32 v7, 7, v35
	v_cndmask_b32_e32 v2, v175, v2, vcc
	v_lshlrev_b32_e32 v8, 8, v52
	s_movk_i32 s6, 0xff90
	v_lshlrev_b32_e32 v0, 1, v3
	v_bfi_b32 v54, -16, v52, v35
	v_lshl_or_b32 v32, v39, 2, v53
	v_lshlrev_b32_e32 v59, 2, v2
	v_add_u32_e32 v2, 0, v8
	v_lshlrev_b32_e32 v9, 5, v7
	v_mul_lo_u32 v4, v52, s6
	v_lshlrev_b32_e32 v10, 4, v7
	s_movk_i32 s6, 0x48
	v_and_b32_e32 v37, 15, v35
	v_and_b32_e32 v5, 2, v0
	v_add_u32_e32 v60, v2, v9
	v_add3_u32 v61, v2, v4, v10
	v_and_b32_e32 v2, 48, v35
	v_mul_lo_u32 v4, v54, s14
	v_mul_lo_u32 v10, v32, s6
	s_add_i32 s6, 0, 0x12000
	v_readlane_b32 s28, v253, 27
	v_readlane_b32 s30, v253, 28
	v_readlane_b32 s7, v253, 29
	v_readlane_b32 s11, v253, 31
	v_add_u32_e32 v62, 0, v2
	v_add_u32_e32 v67, s6, v2
	v_add_u32_e32 v18, s28, v2
	v_add_u32_e32 v19, s30, v2
	v_add3_u32 v69, s7, v4, v2
	v_add3_u32 v70, s11, v4, v2
	v_lshl_or_b32 v2, v5, 4, v37
	v_lshlrev_b32_e32 v21, 6, v32
	v_add_u32_e32 v63, v62, v4
	v_add_u32_e32 v68, v18, v4
	v_or_b32_e32 v4, v21, v2
	v_lshlrev_b32_e32 v4, 2, v4
	v_or_b32_e32 v22, 64, v21
	v_add_u32_e32 v72, 0, v4
	v_add_u32_e32 v73, s11, v4
	v_or_b32_e32 v4, v22, v2
	v_or_b32_e32 v23, 0x80, v21
	v_lshl_add_u32 v74, v4, 2, s11
	v_or_b32_e32 v4, v23, v2
	v_or_b32_e32 v24, 0xc0, v21
	v_lshl_add_u32 v75, v4, 2, s11
	v_or_b32_e32 v4, v24, v2
	v_lshl_add_u32 v76, v4, 2, s11
	v_or_b32_e32 v4, 1, v5
	v_lshlrev_b32_e32 v77, 10, v4
	v_lshl_or_b32 v4, v4, 4, v37
	v_or_b32_e32 v21, v4, v21
	v_lshlrev_b32_e32 v21, 2, v21
	v_add_u32_e32 v78, 0, v21
	v_add_u32_e32 v79, s11, v21
	v_or_b32_e32 v21, v22, v4
	v_lshl_add_u32 v80, v21, 2, s11
	v_or_b32_e32 v21, v23, v4
	v_lshl_add_u32 v81, v21, 2, s11
	v_or_b32_e32 v21, v24, v4
	v_readlane_b32 s31, v253, 32
	v_lshl_add_u32 v82, v21, 2, s11
	v_or_b32_e32 v8, v8, v9
	v_add_u32_e32 v21, 0, v9
	v_add_u32_e32 v86, s31, v9
	v_or_b32_e32 v9, 1, v32
	v_or_b32_e32 v27, 16, v2
	v_and_b32_e32 v6, 63, v35
	v_add_u32_e32 v11, 0x48, v10
	v_add_u32_e32 v12, 0x90, v10
	v_add_u32_e32 v13, 0xd8, v10
	v_lshlrev_b32_e32 v14, 1, v32
	v_cmp_lt_i32_e64 s[52:53], v9, v2
	v_cmp_lt_i32_e64 s[60:61], v9, v27
	v_cmp_eq_u32_e64 s[70:71], v9, v2
	v_cmp_eq_u32_e64 s[78:79], v9, v27
	v_max_i32_e32 v9, 0xe00, v35
	s_lshl_b32 s19, s8, 1
	v_add_u32_e32 v15, s6, v14
	v_cmp_gt_i32_e64 s[8:9], s33, v35
	v_cmp_gt_u32_e32 vcc, 32, v6
	v_lshl_add_u32 v17, v10, 1, s28
	s_movk_i32 s6, 0x240
	v_add_lshl_u32 v23, v2, v10, 1
	v_add_lshl_u32 v24, v11, v2, 1
	v_add_lshl_u32 v25, v12, v2, 1
	v_add_lshl_u32 v26, v13, v2, 1
	v_add_lshl_u32 v10, v27, v10, 1
	v_add_lshl_u32 v11, v11, v27, 1
	v_add_lshl_u32 v12, v12, v27, 1
	v_add_lshl_u32 v13, v13, v27, 1
	v_cmp_eq_u32_e64 s[68:69], 0, v5
	v_sub_u32_e32 v9, v9, v35
	v_writelane_b32 v254, s8, 63
	v_readlane_b32 s10, v253, 30
	v_add_u32_e32 v83, 0, v8
	v_writelane_b32 v255, s9, 0
	v_add_u32_e32 v85, s11, v8
	v_mad_u32_u24 v8, v7, s6, v52
	v_add_u32_e32 v116, s7, v23
	v_add_u32_e32 v117, s7, v24
	v_add_u32_e32 v118, s7, v25
	v_add_u32_e32 v119, s7, v26
	v_add_u32_e32 v148, s7, v10
	v_add_u32_e32 v149, s7, v11
	v_add_u32_e32 v150, s7, v12
	v_add_u32_e32 v151, s7, v13
; __device__ __forceinline__ int ltid() { int t = threadIdx.x; asm volatile("" : "+v"(t)); return t; }
; __device__ __forceinline__ void ph_r7_ca(const P& p, int j, int win, char* smem) {
;     ...
;   const int tid = ltid(), lane = tid & 63, w = tid >> 6, l15 = lane & 15, q4 = lane >> 4, ti = w >> 1, tj0 = (w & 1) * 2;
;   const int c0 = win * 20;
;   for (int it = blockIdx.x; it < 1280; it += gridDim.x) {
;     const int chain = it / 20, cl = it - chain * 20, c = c0 + cl, d = chain & 1, b = chain >> 5, h = (chain >> 1) & 15;
;     {
;       const int rowA = rowmap(d, b, 64 * c + 16 * ti + l15);
;       const float* w0 = p.r7_w0 + (size_t)(j * 2 + d) * 1024 + h * 64; const float* a0 = p.r7_a0 + (size_t)(j * 2 + d) * 1024 + h * 64;
; #pragma unroll
;       for (int tt = 0; tt < 2; tt++) { const int tj = tj0 + tt; f32x4 aw = f32x4{0.f, 0.f, 0.f, 0.f}, aa = aw;
; #pragma unroll
;         for (int ks = 0; ks < 2; ks++) {
;           bf16x8 xw = *(const bf16x8*)(WMb + (size_t)rowA * 128 + d * 64 + 32 * ks + 8 * q4), xa = *(const bf16x8*)(AMb + (size_t)rowA * 128 + d * 64 + 32 * ks + 8 * q4);
;           bf16x8 yw = *(const bf16x8*)(p.W + WR_UP + d * 65536 + (size_t)(h * 64 + 16 * tj + l15) * 64 + 32 * ks + 8 * q4);
;           bf16x8 ya = *(const bf16x8*)(p.W + WR_UP + (2 + d) * 65536 + (size_t)(h * 64 + 16 * tj + l15) * 64 + 32 * ks + 8 * q4);
;           aw = __builtin_amdgcn_mfma_f32_16x16x32_bf16(xw, yw, aw, 0, 0, 0); aa = __builtin_amdgcn_mfma_f32_16x16x32_bf16(xa, ya, aa, 0, 0, 0); }
;         const int ch = 16 * tj + l15; const float w0v = w0[ch], a0v = a0[ch];
; #pragma unroll
;         for (int jj = 0; jj < 4; jj++) { const int tau = 16 * ti + 4 * q4 + jj; LW[tau * 64 + ch] = -0.6065306597126334f * sigm(w0v + aw[jj]); AT[tau * 64 + ch] = sigm(a0v + aa[jj]); }
;       }
;     }
;     __syncthreads();
;     if (tid < 64) { float acc = 0.f;
; #pragma unroll 8
;       for (int t = 0; t < 64; t++) { acc += LW[t * 64 + tid]; LW[t * 64 + tid] = acc; } }
;     __syncthreads();
;     {
;       const int tau = tid >> 3, sc = tid & 7, col = h * 64 + sc * 8; const int row = rowmap(d, b, 64 * c + tau);
;       const bfr* rp = RK + (size_t)row * 4096 + col; uint4 pr = *(const uint4*)rp, pk = *(const uint4*)(rp + 1024);
;       unsigned ur[4] = {pr.x, pr.y, pr.z, pr.w}, uk[4] = {pk.x, pk.y, pk.z, pk.w};
;       float r8[8], k8[8], kr[8];
; #pragma unroll
	s_and_b64 s[6:7], vcc, s[68:69]
	v_add_u32_e32 v9, 0x1ff, v9
	v_add_u32_e32 v128, s11, v11
	v_add_u32_e32 v153, s10, v11
	v_writelane_b32 v255, s6, 1
	v_add_u32_e32 v187, s28, v23
	v_add_u32_e32 v188, s28, v24
	v_add_u32_e32 v189, s28, v25
	v_add_u32_e32 v190, s28, v26
	v_add_u32_e32 v192, s30, v11
	v_add_u32_e32 v195, s28, v10
	v_add_u32_e32 v196, s28, v11
	v_add_u32_e32 v197, s28, v12
	v_add_u32_e32 v198, s28, v13
	v_and_b32_e32 v11, 0x600, v9
	s_movk_i32 s28, 0x600
	v_writelane_b32 v255, s7, 2
	v_cmp_ne_u32_e64 s[8:9], s28, v11
	s_movk_i32 s28, 0x5ff
	v_add_u32_e32 v125, 0, v10
	v_writelane_b32 v255, s8, 3
	v_add_u32_e32 v127, s11, v10
	v_add_u32_e32 v152, s10, v10
	v_add_u32_e32 v191, s30, v10
	v_lshrrev_b32_e32 v10, 9, v9
	v_writelane_b32 v255, s9, 4
	v_cmp_lt_u32_e64 s[8:9], s28, v9
	v_lshrrev_b32_e32 v9, 4, v52
	s_movk_i32 s28, 0x920
	v_mul_lo_u32 v11, v9, s28
	v_lshl_add_u32 v108, v8, 1, 0
	v_mul_u32_u24_e32 v8, 0x48, v2
	v_mul_u32_u24_e32 v28, 0x48, v27
	v_lshl_or_b32 v11, v7, 1, v11
	v_readlane_b32 s28, v253, 33
	v_readlane_b32 s46, v253, 63
	v_bfe_u32 v16, v35, 3, 3
	v_lshlrev_b32_e32 v8, 1, v8
	v_lshlrev_b32_e32 v28, 1, v28
	v_add_u32_e32 v205, s28, v11
	s_movk_i32 s28, 0x1200
	v_lshlrev_b32_e32 v56, 3, v7
	v_cmp_eq_u32_e64 s[46:47], 0, v7
	v_lshl_or_b32 v64, v3, 3, v16
	v_add_u32_e32 v65, 1, v7
	v_lshlrev_b32_e32 v71, 10, v5
	v_add_u32_e32 v111, v15, v8
	v_add_u32_e32 v126, v15, v28
	v_lshl_add_u32 v36, v6, 2, 0
	v_lshlrev_b32_e32 v15, 1, v6
	v_and_b32_e32 v5, 1, v3
	v_mul_lo_u32 v9, v9, s28
	v_mul_u32_u24_e32 v7, 0x120, v7
	v_lshlrev_b32_e32 v3, 5, v3
	v_add_u32_e32 v20, 0, v14
	v_add_u32_e32 v14, s10, v14
	v_sub_u32_e32 v38, v36, v15
	v_mov_b32_e32 v15, s30
	v_add_u32_e32 v10, 1, v10
	v_add3_u32 v3, v9, v7, v3
	v_lshlrev_b32_e32 v0, 3, v39
	v_add_u32_e32 v84, 0xfc00, v21
	v_add_u32_e32 v87, 0xfc04, v21
	v_add_u32_e32 v90, 0xfc08, v21
	v_add_u32_e32 v93, 0xfc0c, v21
	v_add_u32_e32 v96, 0xfc10, v21
	v_add_u32_e32 v99, 0xfc14, v21
	v_add_u32_e32 v102, 0xfc18, v21
	v_add_u32_e32 v105, 0xfc1c, v21
	v_add_u32_e32 v109, v62, v8
	v_or_b32_e32 v21, 2, v32
	v_or_b32_e32 v22, 3, v32
	v_mad_u32_u24 v156, v6, s14, v15
	v_cmp_eq_u32_e64 s[66:67], 1, v5
	v_mul_u32_u24_e32 v5, 0x90, v4
	v_add_u32_e32 v160, v19, v8
	v_add_u32_e32 v161, v20, v8
	v_mul_u32_u24_e32 v15, 0x90, v27
	v_lshlrev_b32_e32 v6, 6, v2
	v_add_u32_e32 v199, v14, v8
	v_add_u32_e32 v200, v18, v8
	v_lshlrev_b32_e32 v8, 6, v27
	v_and_b32_e32 v10, 3, v10
	v_writelane_b32 v255, s8, 5
	v_lshl_or_b32 v3, v16, 2, v3
	v_readlane_b32 s28, v253, 26
	v_lshl_add_u32 v55, v35, 2, 0
	v_cmp_lt_i32_e64 s[42:43], 0, v52
	v_cmp_eq_u32_e64 s[44:45], 63, v52
	v_add_u32_e32 v66, 16, v53
	v_lshl_add_u32 v34, v64, 2, 0
	v_ashrrev_i32_e32 v33, 31, v32
	v_add_u32_e32 v88, 4, v85
	v_add_u32_e32 v89, 4, v86
	v_add_u32_e32 v91, 8, v85
	v_add_u32_e32 v92, 8, v86
	v_add_u32_e32 v94, 12, v85
	v_add_u32_e32 v95, 12, v86
	v_add_u32_e32 v97, 16, v85
	v_add_u32_e32 v98, 16, v86
	v_add_u32_e32 v100, 20, v85
	v_add_u32_e32 v101, 20, v86
	v_add_u32_e32 v103, 24, v85
	v_add_u32_e32 v104, 24, v86
	v_add_u32_e32 v106, 28, v85
	v_add_u32_e32 v107, 28, v86
	v_cmp_lt_i32_e64 s[50:51], v32, v2
	v_cmp_lt_i32_e64 s[54:55], v21, v2
	v_cmp_lt_i32_e64 s[56:57], v22, v2
	v_add_u32_e32 v110, 0, v23
	v_add_u32_e32 v112, s11, v23
	v_add_u32_e32 v113, s11, v24
	v_add_u32_e32 v114, s11, v25
	v_add_u32_e32 v115, s11, v26
	v_add_u32_e32 v120, s10, v23
	v_add_u32_e32 v121, s10, v24
	v_add_u32_e32 v122, s10, v25
	v_add_u32_e32 v123, s10, v26
	v_add_u32_e32 v124, v62, v28
	v_cmp_lt_i32_e64 s[58:59], v32, v27
	v_cmp_lt_i32_e64 s[62:63], v21, v27
	v_cmp_lt_i32_e64 s[64:65], v22, v27
	v_add_u32_e32 v129, s11, v12
	v_add_u32_e32 v147, s11, v13
	v_add_u32_e32 v154, s10, v12
	v_add_u32_e32 v155, s10, v13
	v_mul_u32_u24_e32 v157, 0x90, v2
	v_lshl_add_u32 v158, v2, 1, v17
	s_and_b64 s[6:7], vcc, s[66:67]
	v_lshl_add_u32 v159, v4, 1, v17
	v_add_u32_e32 v162, v19, v28
	v_add_u32_e32 v163, v20, v28
	v_cmp_eq_u32_e64 s[68:69], v32, v2
	v_cmp_eq_u32_e64 s[72:73], v21, v2
	v_cmp_eq_u32_e64 s[74:75], v22, v2
	v_cmp_eq_u32_e64 s[76:77], v32, v27
	v_cmp_eq_u32_e64 s[80:81], v21, v27
	v_cmp_eq_u32_e64 s[82:83], v22, v27
	v_add_u32_e32 v164, s30, v23
	v_add_u32_e32 v165, s30, v24
	v_add_u32_e32 v166, s30, v25
	v_add_u32_e32 v167, s30, v26
	v_add_u32_e32 v193, s30, v12
	v_add_u32_e32 v194, s30, v13
	v_lshl_add_u32 v201, v2, 2, s31
	v_add_u32_e32 v202, v14, v28
	v_add_u32_e32 v203, v18, v28
	v_lshl_add_u32 v204, v27, 2, s31
	v_writelane_b32 v255, s9, 6
	v_add_u32_e32 v206, s28, v3
	v_sub_u32_e32 v207, 0, v10
	v_lshlrev_b32_e32 v40, 1, v0
	v_lshlrev_b32_e32 v208, 2, v2
	v_lshlrev_b32_e32 v209, 2, v4
	v_add_u32_e32 v210, v62, v15
	v_lshlrev_b32_e32 v42, 1, v6
	v_lshlrev_b32_e32 v44, 1, v8
	v_add_u32_e32 v211, v67, v5
	s_branch .LBB0_187

; __global__ void __launch_bounds__(512, 2) mega_kernel(P p) {
;     ...
;   for (int si = 0; si < p.nsched; si++) {
;     run_phase(p, p.sched[si * 3], p.sched[si * 3 + 1], p.sched[si * 3 + 2], dyn_smem);
;     if (si + 1 < p.nsched) { if (p.pad_ != 0) grid.sync(); xcd_barrier(xb); }
.LBB0_1936:
	s_setprio 0
	v_readlane_b32 s6, v253, 36
	s_add_i32 s6, s6, 1
	s_cmp_ge_i32 s6, s97
	v_writelane_b32 v253, s6, 36
	s_cbranch_scc0 .LBB0_1937
	s_getpc_b64 s[98:99]
